# k29: k20 + phase-0 modulation K-loop rewritten: LDS reads batched 7 rows at a time, stage-wise packed FMAs, next weight rows prefetched (strategy 8 latency overlap in a latency-bound loop)
# speedup vs baseline: 1.0008x; 1.0008x over previous
; __device__ __forceinline__ float silu_f(float v) { return v * __builtin_amdgcn_rcpf(1.0f + __expf(-v)); }
; __device__ void phase0(const Params& p, float* lds) {
;     ...
;     for (int it = blockIdx.x; it < 4 * 48; it += gridDim.x) {
;         const int layer = it / 48, cb = it % 48;
;         for (int idx = tid; idx < 33 * 1024; idx += 512) { const int r = idx >> 10, k = idx & 1023; const float v = r < 32 ? p.c[r * 1024 + k] : p.c_ctx[k]; lds[idx] = silu_f(v); }
;         __syncthreads();
;         const float* wp = p.ada_w + (size_t)layer * 1024 * 6144 + cb * 128 + 2 * lane;
;         f32x2 acc[33];
; #pragma unroll
;         for (int r = 0; r < 33; ++r) acc[r] = (f32x2){0.f, 0.f};
; #pragma unroll 1
;         for (int k = wid * 128; k < wid * 128 + 128; k += 4) {
;             const f32x2 w0 = *(const f32x2*)(wp + (size_t)k * 6144), w1 = *(const f32x2*)(wp + (size_t)(k + 1) * 6144), w2 = *(const f32x2*)(wp + (size_t)(k + 2) * 6144), w3 = *(const f32x2*)(wp + (size_t)(k + 3) * 6144);
; #pragma unroll
;             for (int r = 0; r < 33; ++r) { const f32x4 s4 = *(const f32x4*)(lds + r * 1024 + k); acc[r] += w0 * s4[0] + w1 * s4[1] + w2 * s4[2] + w3 * s4[3];
;                 if ((r & 7) == 7) __builtin_amdgcn_sched_barrier(0); }
;         }
.LBB0_17:
	s_or_b64 exec, exec, s[10:11]
	s_mul_hi_i32 s2, s30, 0x2aaaaaab
	s_lshr_b32 s3, s2, 31
	s_ashr_i32 s2, s2, 3
	s_add_i32 s14, s2, s3
	s_mul_i32 s2, s14, 48
	s_sub_i32 s2, s30, s2
	s_lshl_b32 s10, s2, 7
	s_ashr_i32 s11, s10, 31
	s_mul_i32 s13, s14, 0x1800000
	s_lshl_b64 s[2:3], s[10:11], 2
	s_mul_hi_i32 s12, s14, 0x1800000
	s_add_u32 s2, s13, s2
	s_addc_u32 s3, s12, s3
	v_mov_b32_e32 v12, 0
	s_mov_b64 s[12:13], 0
	v_mov_b32_e32 v13, v12
	v_mov_b32_e32 v14, v12
	v_mov_b32_e32 v15, v12
	v_mov_b32_e32 v16, v12
	v_mov_b32_e32 v17, v12
	v_mov_b32_e32 v18, v12
	v_mov_b32_e32 v19, v12
	v_mov_b32_e32 v20, v12
	v_mov_b32_e32 v21, v12
	v_mov_b32_e32 v22, v12
	v_mov_b32_e32 v23, v12
	v_mov_b32_e32 v24, v12
	v_mov_b32_e32 v25, v12
	v_mov_b32_e32 v26, v12
	v_mov_b32_e32 v27, v12
	v_mov_b32_e32 v28, v12
	v_mov_b32_e32 v29, v12
	v_mov_b32_e32 v30, v12
	v_mov_b32_e32 v31, v12
	v_mov_b32_e32 v32, v12
	v_mov_b32_e32 v33, v12
	v_mov_b32_e32 v34, v12
	v_mov_b32_e32 v35, v12
	v_mov_b32_e32 v36, v12
	v_mov_b32_e32 v37, v12
	v_mov_b32_e32 v38, v12
	v_mov_b32_e32 v39, v12
	v_mov_b32_e32 v40, v12
	v_mov_b32_e32 v41, v12
	v_mov_b32_e32 v42, v12
	v_mov_b32_e32 v43, v12
	v_mov_b32_e32 v44, v12
	v_mov_b32_e32 v45, v12
	v_mov_b32_e32 v46, v12
	v_mov_b32_e32 v47, v12
	v_mov_b32_e32 v48, v12
	v_mov_b32_e32 v49, v12
	v_mov_b32_e32 v50, v12
	v_mov_b32_e32 v51, v12
	v_mov_b32_e32 v52, v12
	v_mov_b32_e32 v53, v12
	v_mov_b32_e32 v54, v12
	v_mov_b32_e32 v55, v12
	v_mov_b32_e32 v56, v12
	v_mov_b32_e32 v57, v12
	v_mov_b32_e32 v58, v12
	v_mov_b32_e32 v59, v12
	v_mov_b32_e32 v60, v12
	v_mov_b32_e32 v61, v12
	v_mov_b32_e32 v62, v12
	v_mov_b32_e32 v63, v12
	v_mov_b32_e32 v64, v12
	v_mov_b32_e32 v65, v12
	v_mov_b32_e32 v66, v12
	v_mov_b32_e32 v67, v12
	v_mov_b32_e32 v68, v12
	v_mov_b32_e32 v69, v12
	v_mov_b32_e32 v70, v12
	v_mov_b32_e32 v71, v12
	v_mov_b32_e32 v72, v12
	v_mov_b32_e32 v73, v12
	v_mov_b32_e32 v74, v12
	v_mov_b32_e32 v75, v12
	v_mov_b32_e32 v76, v12
	v_mov_b32_e32 v77, v12
	v_mov_b32_e32 v4, v94
	v_mov_b32_e32 v96, v3
	v_lshl_add_u64 v[78:79], v[10:11], 0, s[2:3]
	s_waitcnt lgkmcnt(0)
	s_barrier
	v_add_co_u32_e64 v120, s[2:3], s24, v78
	s_nop 1
	v_addc_co_u32_e64 v121, s[2:3], -1, v79, s[2:3]
	global_load_dwordx2 v[112:113], v[120:121], off
	v_add_co_u32_e64 v120, s[2:3], s25, v78
	s_nop 1
	v_addc_co_u32_e64 v121, s[2:3], -1, v79, s[2:3]
	global_load_dwordx2 v[114:115], v[120:121], off
	v_add_co_u32_e64 v120, s[2:3], s28, v78
	s_nop 1
	v_addc_co_u32_e64 v121, s[2:3], -1, v79, s[2:3]
	global_load_dwordx2 v[116:117], v[120:121], off
	global_load_dwordx2 v[118:119], v[78:79], off
.LBB0_18:
	s_waitcnt vmcnt(0)
	v_mov_b64_e32 v[80:81], v[112:113]
	v_mov_b64_e32 v[82:83], v[114:115]
	v_mov_b64_e32 v[84:85], v[116:117]
	v_mov_b64_e32 v[86:87], v[118:119]
	v_add_u32_e32 v122, 4, v96
	v_mov_b32_e32 v123, s8
	v_cmp_lt_i32_e32 vcc, v122, v91
	s_nop 1
	v_cndmask_b32_e32 v123, 0, v123, vcc
	s_nop 0
	v_add_co_u32_e32 v124, vcc, v78, v123
	s_nop 1
	v_addc_co_u32_e32 v125, vcc, 0, v79, vcc
	v_add_co_u32_e64 v120, s[2:3], s24, v124
	s_nop 1
	v_addc_co_u32_e64 v121, s[2:3], -1, v125, s[2:3]
	global_load_dwordx2 v[112:113], v[120:121], off
	v_add_co_u32_e64 v120, s[2:3], s25, v124
	s_nop 1
	v_addc_co_u32_e64 v121, s[2:3], -1, v125, s[2:3]
	global_load_dwordx2 v[114:115], v[120:121], off
	v_add_co_u32_e64 v120, s[2:3], s28, v124
	s_nop 1
	v_addc_co_u32_e64 v121, s[2:3], -1, v125, s[2:3]
	global_load_dwordx2 v[116:117], v[120:121], off
	global_load_dwordx2 v[118:119], v[124:125], off
	v_add_u32_e32 v97, 0xfffe0000, v4
	v_add_u32_e32 v102, 0xffff0000, v4
	ds_read_b128 v[126:129], v97
	ds_read_b128 v[130:133], v97 offset:4096
	ds_read_b128 v[134:137], v97 offset:8192
	ds_read_b128 v[138:141], v97 offset:12288
	ds_read_b128 v[142:145], v97 offset:16384
	ds_read_b128 v[146:149], v97 offset:20480
	ds_read_b128 v[150:153], v97 offset:24576
	s_waitcnt lgkmcnt(0)
	v_pk_mul_f32 v[154:155], v[82:83], v[126:127] op_sel:[0,1]
	v_pk_mul_f32 v[156:157], v[82:83], v[130:131] op_sel:[0,1]
	v_pk_mul_f32 v[158:159], v[82:83], v[134:135] op_sel:[0,1]
	v_pk_mul_f32 v[160:161], v[82:83], v[138:139] op_sel:[0,1]
	v_pk_mul_f32 v[162:163], v[82:83], v[142:143] op_sel:[0,1]
	v_pk_mul_f32 v[164:165], v[82:83], v[146:147] op_sel:[0,1]
	v_pk_mul_f32 v[166:167], v[82:83], v[150:151] op_sel:[0,1]
	v_pk_fma_f32 v[154:155], v[80:81], v[126:127], v[154:155] op_sel_hi:[1,0,1]
	v_pk_fma_f32 v[156:157], v[80:81], v[130:131], v[156:157] op_sel_hi:[1,0,1]
	v_pk_fma_f32 v[158:159], v[80:81], v[134:135], v[158:159] op_sel_hi:[1,0,1]
	v_pk_fma_f32 v[160:161], v[80:81], v[138:139], v[160:161] op_sel_hi:[1,0,1]
	v_pk_fma_f32 v[162:163], v[80:81], v[142:143], v[162:163] op_sel_hi:[1,0,1]
	v_pk_fma_f32 v[164:165], v[80:81], v[146:147], v[164:165] op_sel_hi:[1,0,1]
	v_pk_fma_f32 v[166:167], v[80:81], v[150:151], v[166:167] op_sel_hi:[1,0,1]
	v_pk_fma_f32 v[154:155], v[84:85], v[128:129], v[154:155] op_sel_hi:[1,0,1]
	v_pk_fma_f32 v[156:157], v[84:85], v[132:133], v[156:157] op_sel_hi:[1,0,1]
	v_pk_fma_f32 v[158:159], v[84:85], v[136:137], v[158:159] op_sel_hi:[1,0,1]
	v_pk_fma_f32 v[160:161], v[84:85], v[140:141], v[160:161] op_sel_hi:[1,0,1]
	v_pk_fma_f32 v[162:163], v[84:85], v[144:145], v[162:163] op_sel_hi:[1,0,1]
	v_pk_fma_f32 v[164:165], v[84:85], v[148:149], v[164:165] op_sel_hi:[1,0,1]
	v_pk_fma_f32 v[166:167], v[84:85], v[152:153], v[166:167] op_sel_hi:[1,0,1]
	v_mov_b32_e32 v128, v129
	v_mov_b32_e32 v132, v133
	v_mov_b32_e32 v136, v137
	v_mov_b32_e32 v140, v141
	v_mov_b32_e32 v144, v145
	v_mov_b32_e32 v148, v149
	v_mov_b32_e32 v152, v153
	v_pk_fma_f32 v[154:155], v[86:87], v[128:129], v[154:155] op_sel_hi:[1,0,1]
	v_pk_fma_f32 v[156:157], v[86:87], v[132:133], v[156:157] op_sel_hi:[1,0,1]
	v_pk_fma_f32 v[158:159], v[86:87], v[136:137], v[158:159] op_sel_hi:[1,0,1]
	v_pk_fma_f32 v[160:161], v[86:87], v[140:141], v[160:161] op_sel_hi:[1,0,1]
	v_pk_fma_f32 v[162:163], v[86:87], v[144:145], v[162:163] op_sel_hi:[1,0,1]
	v_pk_fma_f32 v[164:165], v[86:87], v[148:149], v[164:165] op_sel_hi:[1,0,1]
	v_pk_fma_f32 v[166:167], v[86:87], v[152:153], v[166:167] op_sel_hi:[1,0,1]
	v_pk_add_f32 v[76:77], v[76:77], v[154:155]
	v_pk_add_f32 v[74:75], v[74:75], v[156:157]
	v_pk_add_f32 v[72:73], v[72:73], v[158:159]
	v_pk_add_f32 v[70:71], v[70:71], v[160:161]
	v_pk_add_f32 v[68:69], v[68:69], v[162:163]
	v_pk_add_f32 v[66:67], v[66:67], v[164:165]
	v_pk_add_f32 v[64:65], v[64:65], v[166:167]
	ds_read_b128 v[126:129], v97 offset:28672
	ds_read_b128 v[130:133], v97 offset:32768
	ds_read_b128 v[134:137], v97 offset:36864
	ds_read_b128 v[138:141], v97 offset:40960
	ds_read_b128 v[142:145], v97 offset:45056
	ds_read_b128 v[146:149], v97 offset:49152
	ds_read_b128 v[150:153], v97 offset:53248
	s_waitcnt lgkmcnt(0)
; __device__ void phase0(const Params& p, float* lds) {
;     ...
;         for (int k = wid * 128; k < wid * 128 + 128; k += 4) {
;             const f32x2 w0 = *(const f32x2*)(wp + (size_t)k * 6144), w1 = *(const f32x2*)(wp + (size_t)(k + 1) * 6144), w2 = *(const f32x2*)(wp + (size_t)(k + 2) * 6144), w3 = *(const f32x2*)(wp + (size_t)(k + 3) * 6144);
; #pragma unroll
;             for (int r = 0; r < 33; ++r) { const f32x4 s4 = *(const f32x4*)(lds + r * 1024 + k); acc[r] += w0 * s4[0] + w1 * s4[1] + w2 * s4[2] + w3 * s4[3];
;                 if ((r & 7) == 7) __builtin_amdgcn_sched_barrier(0); }
;         }
	v_pk_mul_f32 v[154:155], v[82:83], v[126:127] op_sel:[0,1]
	v_pk_mul_f32 v[156:157], v[82:83], v[130:131] op_sel:[0,1]
	v_pk_mul_f32 v[158:159], v[82:83], v[134:135] op_sel:[0,1]
	v_pk_mul_f32 v[160:161], v[82:83], v[138:139] op_sel:[0,1]
	v_pk_mul_f32 v[162:163], v[82:83], v[142:143] op_sel:[0,1]
	v_pk_mul_f32 v[164:165], v[82:83], v[146:147] op_sel:[0,1]
	v_pk_mul_f32 v[166:167], v[82:83], v[150:151] op_sel:[0,1]
	v_pk_fma_f32 v[154:155], v[80:81], v[126:127], v[154:155] op_sel_hi:[1,0,1]
	v_pk_fma_f32 v[156:157], v[80:81], v[130:131], v[156:157] op_sel_hi:[1,0,1]
	v_pk_fma_f32 v[158:159], v[80:81], v[134:135], v[158:159] op_sel_hi:[1,0,1]
	v_pk_fma_f32 v[160:161], v[80:81], v[138:139], v[160:161] op_sel_hi:[1,0,1]
	v_pk_fma_f32 v[162:163], v[80:81], v[142:143], v[162:163] op_sel_hi:[1,0,1]
	v_pk_fma_f32 v[164:165], v[80:81], v[146:147], v[164:165] op_sel_hi:[1,0,1]
	v_pk_fma_f32 v[166:167], v[80:81], v[150:151], v[166:167] op_sel_hi:[1,0,1]
	v_pk_fma_f32 v[154:155], v[84:85], v[128:129], v[154:155] op_sel_hi:[1,0,1]
	v_pk_fma_f32 v[156:157], v[84:85], v[132:133], v[156:157] op_sel_hi:[1,0,1]
	v_pk_fma_f32 v[158:159], v[84:85], v[136:137], v[158:159] op_sel_hi:[1,0,1]
	v_pk_fma_f32 v[160:161], v[84:85], v[140:141], v[160:161] op_sel_hi:[1,0,1]
	v_pk_fma_f32 v[162:163], v[84:85], v[144:145], v[162:163] op_sel_hi:[1,0,1]
	v_pk_fma_f32 v[164:165], v[84:85], v[148:149], v[164:165] op_sel_hi:[1,0,1]
	v_pk_fma_f32 v[166:167], v[84:85], v[152:153], v[166:167] op_sel_hi:[1,0,1]
	v_mov_b32_e32 v128, v129
	v_mov_b32_e32 v132, v133
	v_mov_b32_e32 v136, v137
	v_mov_b32_e32 v140, v141
	v_mov_b32_e32 v144, v145
	v_mov_b32_e32 v148, v149
	v_mov_b32_e32 v152, v153
	v_pk_fma_f32 v[154:155], v[86:87], v[128:129], v[154:155] op_sel_hi:[1,0,1]
	v_pk_fma_f32 v[156:157], v[86:87], v[132:133], v[156:157] op_sel_hi:[1,0,1]
	v_pk_fma_f32 v[158:159], v[86:87], v[136:137], v[158:159] op_sel_hi:[1,0,1]
	v_pk_fma_f32 v[160:161], v[86:87], v[140:141], v[160:161] op_sel_hi:[1,0,1]
	v_pk_fma_f32 v[162:163], v[86:87], v[144:145], v[162:163] op_sel_hi:[1,0,1]
	v_pk_fma_f32 v[164:165], v[86:87], v[148:149], v[164:165] op_sel_hi:[1,0,1]
	v_pk_fma_f32 v[166:167], v[86:87], v[152:153], v[166:167] op_sel_hi:[1,0,1]
	v_pk_add_f32 v[62:63], v[62:63], v[154:155]
	v_pk_add_f32 v[60:61], v[60:61], v[156:157]
	v_pk_add_f32 v[58:59], v[58:59], v[158:159]
	v_pk_add_f32 v[56:57], v[56:57], v[160:161]
	v_pk_add_f32 v[54:55], v[54:55], v[162:163]
	v_pk_add_f32 v[52:53], v[52:53], v[164:165]
	v_pk_add_f32 v[50:51], v[50:51], v[166:167]
	ds_read_b128 v[126:129], v97 offset:57344
	ds_read_b128 v[130:133], v97 offset:61440
	ds_read_b128 v[134:137], v102
	ds_read_b128 v[138:141], v102 offset:4096
	ds_read_b128 v[142:145], v102 offset:8192
	ds_read_b128 v[146:149], v102 offset:12288
	ds_read_b128 v[150:153], v102 offset:16384
	s_waitcnt lgkmcnt(0)
	v_pk_mul_f32 v[154:155], v[82:83], v[126:127] op_sel:[0,1]
	v_pk_mul_f32 v[156:157], v[82:83], v[130:131] op_sel:[0,1]
	v_pk_mul_f32 v[158:159], v[82:83], v[134:135] op_sel:[0,1]
	v_pk_mul_f32 v[160:161], v[82:83], v[138:139] op_sel:[0,1]
	v_pk_mul_f32 v[162:163], v[82:83], v[142:143] op_sel:[0,1]
	v_pk_mul_f32 v[164:165], v[82:83], v[146:147] op_sel:[0,1]
	v_pk_mul_f32 v[166:167], v[82:83], v[150:151] op_sel:[0,1]
	v_pk_fma_f32 v[154:155], v[80:81], v[126:127], v[154:155] op_sel_hi:[1,0,1]
	v_pk_fma_f32 v[156:157], v[80:81], v[130:131], v[156:157] op_sel_hi:[1,0,1]
	v_pk_fma_f32 v[158:159], v[80:81], v[134:135], v[158:159] op_sel_hi:[1,0,1]
	v_pk_fma_f32 v[160:161], v[80:81], v[138:139], v[160:161] op_sel_hi:[1,0,1]
	v_pk_fma_f32 v[162:163], v[80:81], v[142:143], v[162:163] op_sel_hi:[1,0,1]
	v_pk_fma_f32 v[164:165], v[80:81], v[146:147], v[164:165] op_sel_hi:[1,0,1]
	v_pk_fma_f32 v[166:167], v[80:81], v[150:151], v[166:167] op_sel_hi:[1,0,1]
	v_pk_fma_f32 v[154:155], v[84:85], v[128:129], v[154:155] op_sel_hi:[1,0,1]
	v_pk_fma_f32 v[156:157], v[84:85], v[132:133], v[156:157] op_sel_hi:[1,0,1]
	v_pk_fma_f32 v[158:159], v[84:85], v[136:137], v[158:159] op_sel_hi:[1,0,1]
	v_pk_fma_f32 v[160:161], v[84:85], v[140:141], v[160:161] op_sel_hi:[1,0,1]
	v_pk_fma_f32 v[162:163], v[84:85], v[144:145], v[162:163] op_sel_hi:[1,0,1]
	v_pk_fma_f32 v[164:165], v[84:85], v[148:149], v[164:165] op_sel_hi:[1,0,1]
	v_pk_fma_f32 v[166:167], v[84:85], v[152:153], v[166:167] op_sel_hi:[1,0,1]
	v_mov_b32_e32 v128, v129
	v_mov_b32_e32 v132, v133
	v_mov_b32_e32 v136, v137
	v_mov_b32_e32 v140, v141
	v_mov_b32_e32 v144, v145
	v_mov_b32_e32 v148, v149
	v_mov_b32_e32 v152, v153
	v_pk_fma_f32 v[154:155], v[86:87], v[128:129], v[154:155] op_sel_hi:[1,0,1]
	v_pk_fma_f32 v[156:157], v[86:87], v[132:133], v[156:157] op_sel_hi:[1,0,1]
	v_pk_fma_f32 v[158:159], v[86:87], v[136:137], v[158:159] op_sel_hi:[1,0,1]
	v_pk_fma_f32 v[160:161], v[86:87], v[140:141], v[160:161] op_sel_hi:[1,0,1]
	v_pk_fma_f32 v[162:163], v[86:87], v[144:145], v[162:163] op_sel_hi:[1,0,1]
	v_pk_fma_f32 v[164:165], v[86:87], v[148:149], v[164:165] op_sel_hi:[1,0,1]
	v_pk_fma_f32 v[166:167], v[86:87], v[152:153], v[166:167] op_sel_hi:[1,0,1]
	v_pk_add_f32 v[48:49], v[48:49], v[154:155]
	v_pk_add_f32 v[46:47], v[46:47], v[156:157]
	v_pk_add_f32 v[44:45], v[44:45], v[158:159]
	v_pk_add_f32 v[42:43], v[42:43], v[160:161]
	v_pk_add_f32 v[40:41], v[40:41], v[162:163]
	v_pk_add_f32 v[38:39], v[38:39], v[164:165]
	v_pk_add_f32 v[36:37], v[36:37], v[166:167]
	ds_read_b128 v[126:129], v102 offset:20480
	ds_read_b128 v[130:133], v102 offset:24576
	ds_read_b128 v[134:137], v102 offset:28672
	ds_read_b128 v[138:141], v102 offset:32768
	ds_read_b128 v[142:145], v102 offset:36864
	ds_read_b128 v[146:149], v102 offset:40960
	ds_read_b128 v[150:153], v102 offset:45056
	s_waitcnt lgkmcnt(0)
; __device__ void phase0(const Params& p, float* lds) {
;     ...
;         for (int k = wid * 128; k < wid * 128 + 128; k += 4) {
;             const f32x2 w0 = *(const f32x2*)(wp + (size_t)k * 6144), w1 = *(const f32x2*)(wp + (size_t)(k + 1) * 6144), w2 = *(const f32x2*)(wp + (size_t)(k + 2) * 6144), w3 = *(const f32x2*)(wp + (size_t)(k + 3) * 6144);
; #pragma unroll
;             for (int r = 0; r < 33; ++r) { const f32x4 s4 = *(const f32x4*)(lds + r * 1024 + k); acc[r] += w0 * s4[0] + w1 * s4[1] + w2 * s4[2] + w3 * s4[3];
;                 if ((r & 7) == 7) __builtin_amdgcn_sched_barrier(0); }
;         }
;         __syncthreads();
; #pragma unroll
;         for (int r = 0; r < 33; ++r) *(f32x2*)(lds + (wid * 33 + r) * 128 + 2 * lane) = acc[r];
	v_pk_mul_f32 v[154:155], v[82:83], v[126:127] op_sel:[0,1]
	v_pk_mul_f32 v[156:157], v[82:83], v[130:131] op_sel:[0,1]
	v_pk_mul_f32 v[158:159], v[82:83], v[134:135] op_sel:[0,1]
	v_pk_mul_f32 v[160:161], v[82:83], v[138:139] op_sel:[0,1]
	v_pk_mul_f32 v[162:163], v[82:83], v[142:143] op_sel:[0,1]
	v_pk_mul_f32 v[164:165], v[82:83], v[146:147] op_sel:[0,1]
	v_pk_mul_f32 v[166:167], v[82:83], v[150:151] op_sel:[0,1]
	v_pk_fma_f32 v[154:155], v[80:81], v[126:127], v[154:155] op_sel_hi:[1,0,1]
	v_pk_fma_f32 v[156:157], v[80:81], v[130:131], v[156:157] op_sel_hi:[1,0,1]
	v_pk_fma_f32 v[158:159], v[80:81], v[134:135], v[158:159] op_sel_hi:[1,0,1]
	v_pk_fma_f32 v[160:161], v[80:81], v[138:139], v[160:161] op_sel_hi:[1,0,1]
	v_pk_fma_f32 v[162:163], v[80:81], v[142:143], v[162:163] op_sel_hi:[1,0,1]
	v_pk_fma_f32 v[164:165], v[80:81], v[146:147], v[164:165] op_sel_hi:[1,0,1]
	v_pk_fma_f32 v[166:167], v[80:81], v[150:151], v[166:167] op_sel_hi:[1,0,1]
	v_pk_fma_f32 v[154:155], v[84:85], v[128:129], v[154:155] op_sel_hi:[1,0,1]
	v_pk_fma_f32 v[156:157], v[84:85], v[132:133], v[156:157] op_sel_hi:[1,0,1]
	v_pk_fma_f32 v[158:159], v[84:85], v[136:137], v[158:159] op_sel_hi:[1,0,1]
	v_pk_fma_f32 v[160:161], v[84:85], v[140:141], v[160:161] op_sel_hi:[1,0,1]
	v_pk_fma_f32 v[162:163], v[84:85], v[144:145], v[162:163] op_sel_hi:[1,0,1]
	v_pk_fma_f32 v[164:165], v[84:85], v[148:149], v[164:165] op_sel_hi:[1,0,1]
	v_pk_fma_f32 v[166:167], v[84:85], v[152:153], v[166:167] op_sel_hi:[1,0,1]
	v_mov_b32_e32 v128, v129
	v_mov_b32_e32 v132, v133
	v_mov_b32_e32 v136, v137
	v_mov_b32_e32 v140, v141
	v_mov_b32_e32 v144, v145
	v_mov_b32_e32 v148, v149
	v_mov_b32_e32 v152, v153
	v_pk_fma_f32 v[154:155], v[86:87], v[128:129], v[154:155] op_sel_hi:[1,0,1]
	v_pk_fma_f32 v[156:157], v[86:87], v[132:133], v[156:157] op_sel_hi:[1,0,1]
	v_pk_fma_f32 v[158:159], v[86:87], v[136:137], v[158:159] op_sel_hi:[1,0,1]
	v_pk_fma_f32 v[160:161], v[86:87], v[140:141], v[160:161] op_sel_hi:[1,0,1]
	v_pk_fma_f32 v[162:163], v[86:87], v[144:145], v[162:163] op_sel_hi:[1,0,1]
	v_pk_fma_f32 v[164:165], v[86:87], v[148:149], v[164:165] op_sel_hi:[1,0,1]
	v_pk_fma_f32 v[166:167], v[86:87], v[152:153], v[166:167] op_sel_hi:[1,0,1]
	v_pk_add_f32 v[34:35], v[34:35], v[154:155]
	v_pk_add_f32 v[32:33], v[32:33], v[156:157]
	v_pk_add_f32 v[30:31], v[30:31], v[158:159]
	v_pk_add_f32 v[28:29], v[28:29], v[160:161]
	v_pk_add_f32 v[26:27], v[26:27], v[162:163]
	v_pk_add_f32 v[24:25], v[24:25], v[164:165]
	v_pk_add_f32 v[22:23], v[22:23], v[166:167]
	ds_read_b128 v[126:129], v102 offset:49152
	ds_read_b128 v[130:133], v102 offset:53248
	ds_read_b128 v[134:137], v102 offset:57344
	ds_read_b128 v[138:141], v102 offset:61440
	ds_read_b128 v[142:145], v4
	s_waitcnt lgkmcnt(0)
	v_pk_mul_f32 v[154:155], v[82:83], v[126:127] op_sel:[0,1]
	v_pk_mul_f32 v[156:157], v[82:83], v[130:131] op_sel:[0,1]
	v_pk_mul_f32 v[158:159], v[82:83], v[134:135] op_sel:[0,1]
	v_pk_mul_f32 v[160:161], v[82:83], v[138:139] op_sel:[0,1]
	v_pk_mul_f32 v[162:163], v[82:83], v[142:143] op_sel:[0,1]
	v_pk_fma_f32 v[154:155], v[80:81], v[126:127], v[154:155] op_sel_hi:[1,0,1]
	v_pk_fma_f32 v[156:157], v[80:81], v[130:131], v[156:157] op_sel_hi:[1,0,1]
	v_pk_fma_f32 v[158:159], v[80:81], v[134:135], v[158:159] op_sel_hi:[1,0,1]
	v_pk_fma_f32 v[160:161], v[80:81], v[138:139], v[160:161] op_sel_hi:[1,0,1]
	v_pk_fma_f32 v[162:163], v[80:81], v[142:143], v[162:163] op_sel_hi:[1,0,1]
	v_pk_fma_f32 v[154:155], v[84:85], v[128:129], v[154:155] op_sel_hi:[1,0,1]
	v_pk_fma_f32 v[156:157], v[84:85], v[132:133], v[156:157] op_sel_hi:[1,0,1]
	v_pk_fma_f32 v[158:159], v[84:85], v[136:137], v[158:159] op_sel_hi:[1,0,1]
	v_pk_fma_f32 v[160:161], v[84:85], v[140:141], v[160:161] op_sel_hi:[1,0,1]
	v_pk_fma_f32 v[162:163], v[84:85], v[144:145], v[162:163] op_sel_hi:[1,0,1]
	v_mov_b32_e32 v128, v129
	v_mov_b32_e32 v132, v133
	v_mov_b32_e32 v136, v137
	v_mov_b32_e32 v140, v141
	v_mov_b32_e32 v144, v145
	v_pk_fma_f32 v[154:155], v[86:87], v[128:129], v[154:155] op_sel_hi:[1,0,1]
	v_pk_fma_f32 v[156:157], v[86:87], v[132:133], v[156:157] op_sel_hi:[1,0,1]
	v_pk_fma_f32 v[158:159], v[86:87], v[136:137], v[158:159] op_sel_hi:[1,0,1]
	v_pk_fma_f32 v[160:161], v[86:87], v[140:141], v[160:161] op_sel_hi:[1,0,1]
	v_pk_fma_f32 v[162:163], v[86:87], v[144:145], v[162:163] op_sel_hi:[1,0,1]
	v_pk_add_f32 v[20:21], v[20:21], v[154:155]
	v_pk_add_f32 v[18:19], v[18:19], v[156:157]
	v_pk_add_f32 v[16:17], v[16:17], v[158:159]
	v_pk_add_f32 v[14:15], v[14:15], v[160:161]
	v_pk_add_f32 v[12:13], v[12:13], v[162:163]
	v_add_u32_e32 v96, 4, v96
	v_cmp_ge_i32_e64 s[2:3], v96, v91
	v_add_u32_e32 v4, 16, v4
	v_lshl_add_u64 v[78:79], v[78:79], 0, s[8:9]
	s_nop 1
	s_or_b64 s[12:13], s[2:3], s[12:13]
	s_andn2_b64 exec, exec, s[12:13]
	s_cbranch_execnz .LBB0_18
	s_or_b64 exec, exec, s[12:13]
	s_barrier
	ds_write2st64_b64 v95, v[76:77], v[74:75] offset1:1
	ds_write2st64_b64 v95, v[72:73], v[70:71] offset0:2 offset1:3
	ds_write2st64_b64 v95, v[68:69], v[66:67] offset0:4 offset1:5
	ds_write2st64_b64 v95, v[64:65], v[62:63] offset0:6 offset1:7
	ds_write2st64_b64 v95, v[60:61], v[58:59] offset0:8 offset1:9
	ds_write2st64_b64 v95, v[56:57], v[54:55] offset0:10 offset1:11
	ds_write2st64_b64 v95, v[52:53], v[50:51] offset0:12 offset1:13
	ds_write2st64_b64 v95, v[48:49], v[46:47] offset0:14 offset1:15
	ds_write2st64_b64 v95, v[44:45], v[42:43] offset0:16 offset1:17
	ds_write2st64_b64 v95, v[40:41], v[38:39] offset0:18 offset1:19
	ds_write2st64_b64 v95, v[36:37], v[34:35] offset0:20 offset1:21
	ds_write2st64_b64 v95, v[32:33], v[30:31] offset0:22 offset1:23
	ds_write2st64_b64 v95, v[28:29], v[26:27] offset0:24 offset1:25
	ds_write2st64_b64 v95, v[24:25], v[22:23] offset0:26 offset1:27
	ds_write2st64_b64 v95, v[20:21], v[18:19] offset0:28 offset1:29
	ds_write2st64_b64 v95, v[16:17], v[14:15] offset0:30 offset1:31
	ds_write_b64 v95, v[12:13] offset:16384
	s_waitcnt lgkmcnt(0)
	s_barrier
	s_and_saveexec_b64 s[12:13], s[0:1]
	s_cbranch_execz .LBB0_13
	s_mul_i32 s2, s14, 0x1800
	s_add_i32 s2, s2, s10
	v_or_b32_e32 v12, s2, v90
	v_readlane_b32 s68, v254, 6
	v_ashrrev_i32_e32 v13, 31, v12
	v_readlane_b32 s78, v254, 16
	v_readlane_b32 s79, v254, 17
	s_mul_hi_i32 s15, s14, 33
	s_mul_i32 s14, s14, 33
	v_lshl_add_u64 v[12:13], v[12:13], 2, s[78:79]
	v_lshl_add_u64 v[14:15], s[10:11], 2, v[6:7]
	s_mov_b64 s[10:11], 0
	v_mov_b32_e32 v4, v2
	v_readlane_b32 s69, v254, 7
	v_readlane_b32 s70, v254, 8
	v_readlane_b32 s71, v254, 9
	v_readlane_b32 s72, v254, 10
	v_readlane_b32 s73, v254, 11
	v_readlane_b32 s74, v254, 12
	v_readlane_b32 s75, v254, 13
	v_readlane_b32 s76, v254, 14
	v_readlane_b32 s77, v254, 15
	v_readlane_b32 s80, v254, 18
	v_readlane_b32 s81, v254, 19
	v_readlane_b32 s82, v254, 20
	v_readlane_b32 s83, v254, 21
